# FFN-down sample-row tiles: hand-written k-loop, both fragment buffers prefetched one chunk ahead, the two 64-byte halves of a line requested by adjacent loads
# speedup vs baseline: 1.0176x; 1.0000x over previous
; #define SK_LD(bu, PA, PB) do { _Pragma("unroll") for (int k_ = 0; k_ < 2; ++k_) _Pragma("unroll") for (int i_ = 0; i_ < 4; ++i_) { fa[bu][k_][i_] = *(const bf16x8*)((PA) + va[i_] + k_ * 64); fb[bu][k_][i_] = *(const bf16x8*)((PB) + vb[i_] + k_ * 64); } } while (0)
; #define SK_MM(bu) do { _Pragma("unroll") for (int k_ = 0; k_ < 2; ++k_) _Pragma("unroll") for (int m_ = 0; m_ < 4; ++m_) _Pragma("unroll") for (int n_ = 0; n_ < 4; ++n_) acc[m_][n_] = mfma16(fb[bu][k_][n_], fa[bu][k_][m_], acc[m_][n_]); } while (0)
; __device__ __forceinline__ void skinny_kloop(f32x4 (&acc)[4][4], const char* pa, const char* pb, const unsigned (&va)[4], const unsigned (&vb)[4], const int nc) {
;     bf16x8 fa[2][2][4], fb[2][2][4];
;     ...
;     SK_LD(0, pa, pb);
; #pragma unroll 1
;     for (int c = 0; c < nc; c += 2) {
;         const int o1 = (c + 1 < nc) ? 128 : 0, o2 = (c + 2 < nc) ? 256 : 0;
;         SK_LD(1, pa + o1, pb + o1);
;         SK_MM(0);
;         SK_LD(0, pa + o2, pb + o2);
;         if (c + 1 < nc) SK_MM(1);
; template <class Pre, class Fin>
; __device__ __forceinline__ void skinny_tiles(const int tid, LAS unsigned char* lds, const bf16_t* A, const int lda, const bf16_t* Bt, const int ldb, const int kch0, const int nc, const int G, const int bid, const Pre& pre, const Fin& fin) {
;     ...
;     for (int i = 0; i < 4; ++i) { va[i] = (unsigned)((16 * i + fr) * lda + 8 * fq) * 2u; vb[i] = (unsigned)((16 * i + fr) * ldb + 8 * fq) * 2u; }
;     for (int t = bid; t < 256; t += G) {
;         const int x = t & 7, j = t >> 3, row0 = (j >> 2) * 64, col0 = (x * 4 + (j & 3)) * 64;
;         f32x4 acc[4][4];
; #pragma unroll
;         for (int m = 0; m < 4; ++m)
; #pragma unroll
;             for (int n = 0; n < 4; ++n) acc[m][n] = (f32x4){0.f, 0.f, 0.f, 0.f};
;         skinny_kloop(acc, (const char*)(A + (size_t)row0 * lda + kch0 * 64), (const char*)(Bt + (size_t)col0 * ldb + kch0 * 64), va, vb, nc);
.LBB0_5687:
	s_bfe_u32 s0, s28, 0x30002
	s_bfe_u32 s1, s30, 0x20003
	s_mul_i32 s0, s0, 0x160000
	s_mul_i32 s4, s1, 0x58000
	s_add_i32 s0, s0, s4
	s_lshl_b32 s26, s0, 1
	s_lshl_b32 s31, s30, 1
	s_lshl_b32 s0, s30, 2
	s_and_b32 s0, s0, 28
	s_andn2_b32 s31, s31, 63
	s_or_b32 s34, s0, s1
	s_mul_i32 s0, s31, 0x2c00
	s_mul_hi_i32 s1, s31, 0x2c00
	s_add_u32 s0, s18, s0
	s_addc_u32 s1, s19, s1
	s_mul_i32 s4, s34, 0xb0000
	s_add_u32 s4, s14, s4
	s_addc_u32 s5, s15, 0
	global_load_dwordx4 v[0:3], v132, s[0:1] offset:0
	global_load_dwordx4 v[88:91], v132, s[0:1] offset:64
	global_load_dwordx4 v[4:7], v132, s[4:5] offset:0
	global_load_dwordx4 v[84:87], v132, s[4:5] offset:64
	global_load_dwordx4 v[12:15], v138, s[0:1] offset:0
	global_load_dwordx4 v[92:95], v138, s[0:1] offset:64
	global_load_dwordx4 v[24:27], v138, s[4:5] offset:0
	global_load_dwordx4 v[96:99], v138, s[4:5] offset:64
	global_load_dwordx4 v[28:31], v136, s[0:1] offset:0
	global_load_dwordx4 v[100:103], v136, s[0:1] offset:64
	global_load_dwordx4 v[36:39], v136, s[4:5] offset:0
	global_load_dwordx4 v[104:107], v136, s[4:5] offset:64
	global_load_dwordx4 v[40:43], v134, s[0:1] offset:0
	global_load_dwordx4 v[112:115], v134, s[0:1] offset:64
	global_load_dwordx4 v[80:83], v134, s[4:5] offset:0
	global_load_dwordx4 v[120:123], v134, s[4:5] offset:64
	global_load_dwordx4 v[140:143], v132, s[0:1] offset:128
	global_load_dwordx4 v[172:175], v132, s[0:1] offset:192
	global_load_dwordx4 v[156:159], v132, s[4:5] offset:128
	global_load_dwordx4 v[204:207], v132, s[4:5] offset:192
	global_load_dwordx4 v[144:147], v138, s[0:1] offset:128
	global_load_dwordx4 v[192:195], v138, s[0:1] offset:192
	global_load_dwordx4 v[160:163], v138, s[4:5] offset:128
	global_load_dwordx4 v[208:211], v138, s[4:5] offset:192
	global_load_dwordx4 v[148:151], v136, s[0:1] offset:128
	global_load_dwordx4 v[196:199], v136, s[0:1] offset:192
	global_load_dwordx4 v[164:167], v136, s[4:5] offset:128
	global_load_dwordx4 v[212:215], v136, s[4:5] offset:192
	global_load_dwordx4 v[152:155], v134, s[0:1] offset:128
	global_load_dwordx4 v[200:203], v134, s[0:1] offset:192
	global_load_dwordx4 v[168:171], v134, s[4:5] offset:128
	global_load_dwordx4 v[216:219], v134, s[4:5] offset:192
	s_waitcnt vmcnt(16)
	v_mfma_f32_16x16x32_bf16 v[20:23], v[4:7], v[0:3], 0
	v_mfma_f32_16x16x32_bf16 v[72:75], v[24:27], v[0:3], 0
	v_mfma_f32_16x16x32_bf16 v[68:71], v[36:39], v[0:3], 0
	v_mfma_f32_16x16x32_bf16 v[60:63], v[80:83], v[0:3], 0
	v_mfma_f32_16x16x32_bf16 v[16:19], v[4:7], v[12:15], 0
	v_mfma_f32_16x16x32_bf16 v[52:55], v[24:27], v[12:15], 0
	v_mfma_f32_16x16x32_bf16 v[56:59], v[36:39], v[12:15], 0
	v_mfma_f32_16x16x32_bf16 v[48:51], v[80:83], v[12:15], 0
	v_mfma_f32_16x16x32_bf16 v[8:11], v[4:7], v[28:31], 0
	v_mfma_f32_16x16x32_bf16 v[44:47], v[24:27], v[28:31], 0
	v_mfma_f32_16x16x32_bf16 v[64:67], v[36:39], v[28:31], 0
	v_mfma_f32_16x16x32_bf16 v[76:79], v[80:83], v[28:31], 0
	v_mfma_f32_16x16x32_bf16 v[108:111], v[4:7], v[40:43], 0
	v_mfma_f32_16x16x32_bf16 v[116:119], v[24:27], v[40:43], 0
	v_mfma_f32_16x16x32_bf16 v[124:127], v[36:39], v[40:43], 0
	v_mfma_f32_16x16x32_bf16 v[128:131], v[80:83], v[40:43], 0
	v_mfma_f32_16x16x32_bf16 v[20:23], v[84:87], v[88:91], v[20:23]
	v_mfma_f32_16x16x32_bf16 v[72:75], v[96:99], v[88:91], v[72:75]
	v_mfma_f32_16x16x32_bf16 v[68:71], v[104:107], v[88:91], v[68:71]
	v_mfma_f32_16x16x32_bf16 v[60:63], v[120:123], v[88:91], v[60:63]
	v_mfma_f32_16x16x32_bf16 v[16:19], v[84:87], v[92:95], v[16:19]
	v_mfma_f32_16x16x32_bf16 v[52:55], v[96:99], v[92:95], v[52:55]
	v_mfma_f32_16x16x32_bf16 v[56:59], v[104:107], v[92:95], v[56:59]
	v_mfma_f32_16x16x32_bf16 v[48:51], v[120:123], v[92:95], v[48:51]
	v_mfma_f32_16x16x32_bf16 v[8:11], v[84:87], v[100:103], v[8:11]
	v_mfma_f32_16x16x32_bf16 v[44:47], v[96:99], v[100:103], v[44:47]
	v_mfma_f32_16x16x32_bf16 v[64:67], v[104:107], v[100:103], v[64:67]
	v_mfma_f32_16x16x32_bf16 v[76:79], v[120:123], v[100:103], v[76:79]
	v_mfma_f32_16x16x32_bf16 v[108:111], v[84:87], v[112:115], v[108:111]
	v_mfma_f32_16x16x32_bf16 v[116:119], v[96:99], v[112:115], v[116:119]
	v_mfma_f32_16x16x32_bf16 v[124:127], v[104:107], v[112:115], v[124:127]
	v_mfma_f32_16x16x32_bf16 v[128:131], v[120:123], v[112:115], v[128:131]
	global_load_dwordx4 v[0:3], v132, s[0:1] offset:256
	global_load_dwordx4 v[88:91], v132, s[0:1] offset:320
	global_load_dwordx4 v[4:7], v132, s[4:5] offset:256
	global_load_dwordx4 v[84:87], v132, s[4:5] offset:320
	global_load_dwordx4 v[12:15], v138, s[0:1] offset:256
	global_load_dwordx4 v[92:95], v138, s[0:1] offset:320
	global_load_dwordx4 v[24:27], v138, s[4:5] offset:256
	global_load_dwordx4 v[96:99], v138, s[4:5] offset:320
	global_load_dwordx4 v[28:31], v136, s[0:1] offset:256
	global_load_dwordx4 v[100:103], v136, s[0:1] offset:320
	global_load_dwordx4 v[36:39], v136, s[4:5] offset:256
	global_load_dwordx4 v[104:107], v136, s[4:5] offset:320
	global_load_dwordx4 v[40:43], v134, s[0:1] offset:256
	global_load_dwordx4 v[112:115], v134, s[0:1] offset:320
	global_load_dwordx4 v[80:83], v134, s[4:5] offset:256
	global_load_dwordx4 v[120:123], v134, s[4:5] offset:320
	s_waitcnt vmcnt(16)
; #define SK_LD(bu, PA, PB) do { _Pragma("unroll") for (int k_ = 0; k_ < 2; ++k_) _Pragma("unroll") for (int i_ = 0; i_ < 4; ++i_) { fa[bu][k_][i_] = *(const bf16x8*)((PA) + va[i_] + k_ * 64); fb[bu][k_][i_] = *(const bf16x8*)((PB) + vb[i_] + k_ * 64); } } while (0)
; #define SK_MM(bu) do { _Pragma("unroll") for (int k_ = 0; k_ < 2; ++k_) _Pragma("unroll") for (int m_ = 0; m_ < 4; ++m_) _Pragma("unroll") for (int n_ = 0; n_ < 4; ++n_) acc[m_][n_] = mfma16(fb[bu][k_][n_], fa[bu][k_][m_], acc[m_][n_]); } while (0)
; __device__ __forceinline__ void skinny_kloop(f32x4 (&acc)[4][4], const char* pa, const char* pb, const unsigned (&va)[4], const unsigned (&vb)[4], const int nc) {
;     bf16x8 fa[2][2][4], fb[2][2][4];
;     ...
;     SK_LD(0, pa, pb);
; #pragma unroll 1
;     for (int c = 0; c < nc; c += 2) {
;         const int o1 = (c + 1 < nc) ? 128 : 0, o2 = (c + 2 < nc) ? 256 : 0;
;         SK_LD(1, pa + o1, pb + o1);
;         SK_MM(0);
;         SK_LD(0, pa + o2, pb + o2);
;         if (c + 1 < nc) SK_MM(1);
;         pa += 256; pb += 256;
;     }
	v_mfma_f32_16x16x32_bf16 v[20:23], v[156:159], v[140:143], v[20:23]
	v_mfma_f32_16x16x32_bf16 v[72:75], v[160:163], v[140:143], v[72:75]
	v_mfma_f32_16x16x32_bf16 v[68:71], v[164:167], v[140:143], v[68:71]
	v_mfma_f32_16x16x32_bf16 v[60:63], v[168:171], v[140:143], v[60:63]
	v_mfma_f32_16x16x32_bf16 v[16:19], v[156:159], v[144:147], v[16:19]
	v_mfma_f32_16x16x32_bf16 v[52:55], v[160:163], v[144:147], v[52:55]
	v_mfma_f32_16x16x32_bf16 v[56:59], v[164:167], v[144:147], v[56:59]
	v_mfma_f32_16x16x32_bf16 v[48:51], v[168:171], v[144:147], v[48:51]
	v_mfma_f32_16x16x32_bf16 v[8:11], v[156:159], v[148:151], v[8:11]
	v_mfma_f32_16x16x32_bf16 v[44:47], v[160:163], v[148:151], v[44:47]
	v_mfma_f32_16x16x32_bf16 v[64:67], v[164:167], v[148:151], v[64:67]
	v_mfma_f32_16x16x32_bf16 v[76:79], v[168:171], v[148:151], v[76:79]
	v_mfma_f32_16x16x32_bf16 v[108:111], v[156:159], v[152:155], v[108:111]
	v_mfma_f32_16x16x32_bf16 v[116:119], v[160:163], v[152:155], v[116:119]
	v_mfma_f32_16x16x32_bf16 v[124:127], v[164:167], v[152:155], v[124:127]
	v_mfma_f32_16x16x32_bf16 v[128:131], v[168:171], v[152:155], v[128:131]
	v_mfma_f32_16x16x32_bf16 v[20:23], v[204:207], v[172:175], v[20:23]
	v_mfma_f32_16x16x32_bf16 v[72:75], v[208:211], v[172:175], v[72:75]
	v_mfma_f32_16x16x32_bf16 v[68:71], v[212:215], v[172:175], v[68:71]
	v_mfma_f32_16x16x32_bf16 v[60:63], v[216:219], v[172:175], v[60:63]
	v_mfma_f32_16x16x32_bf16 v[16:19], v[204:207], v[192:195], v[16:19]
	v_mfma_f32_16x16x32_bf16 v[52:55], v[208:211], v[192:195], v[52:55]
	v_mfma_f32_16x16x32_bf16 v[56:59], v[212:215], v[192:195], v[56:59]
	v_mfma_f32_16x16x32_bf16 v[48:51], v[216:219], v[192:195], v[48:51]
	v_mfma_f32_16x16x32_bf16 v[8:11], v[204:207], v[196:199], v[8:11]
	v_mfma_f32_16x16x32_bf16 v[44:47], v[208:211], v[196:199], v[44:47]
	v_mfma_f32_16x16x32_bf16 v[64:67], v[212:215], v[196:199], v[64:67]
	v_mfma_f32_16x16x32_bf16 v[76:79], v[216:219], v[196:199], v[76:79]
	v_mfma_f32_16x16x32_bf16 v[108:111], v[204:207], v[200:203], v[108:111]
	v_mfma_f32_16x16x32_bf16 v[116:119], v[208:211], v[200:203], v[116:119]
	v_mfma_f32_16x16x32_bf16 v[124:127], v[212:215], v[200:203], v[124:127]
	v_mfma_f32_16x16x32_bf16 v[128:131], v[216:219], v[200:203], v[128:131]
	global_load_dwordx4 v[140:143], v132, s[0:1] offset:384
	global_load_dwordx4 v[172:175], v132, s[0:1] offset:448
	global_load_dwordx4 v[156:159], v132, s[4:5] offset:384
	global_load_dwordx4 v[204:207], v132, s[4:5] offset:448
	global_load_dwordx4 v[144:147], v138, s[0:1] offset:384
	global_load_dwordx4 v[192:195], v138, s[0:1] offset:448
	global_load_dwordx4 v[160:163], v138, s[4:5] offset:384
	global_load_dwordx4 v[208:211], v138, s[4:5] offset:448
	global_load_dwordx4 v[148:151], v136, s[0:1] offset:384
	global_load_dwordx4 v[196:199], v136, s[0:1] offset:448
	global_load_dwordx4 v[164:167], v136, s[4:5] offset:384
	global_load_dwordx4 v[212:215], v136, s[4:5] offset:448
	global_load_dwordx4 v[152:155], v134, s[0:1] offset:384
	global_load_dwordx4 v[200:203], v134, s[0:1] offset:448
	global_load_dwordx4 v[168:171], v134, s[4:5] offset:384
	global_load_dwordx4 v[216:219], v134, s[4:5] offset:448
	s_waitcnt vmcnt(16)
	v_mfma_f32_16x16x32_bf16 v[20:23], v[4:7], v[0:3], v[20:23]
	v_mfma_f32_16x16x32_bf16 v[72:75], v[24:27], v[0:3], v[72:75]
	v_mfma_f32_16x16x32_bf16 v[68:71], v[36:39], v[0:3], v[68:71]
	v_mfma_f32_16x16x32_bf16 v[60:63], v[80:83], v[0:3], v[60:63]
	v_mfma_f32_16x16x32_bf16 v[16:19], v[4:7], v[12:15], v[16:19]
	v_mfma_f32_16x16x32_bf16 v[52:55], v[24:27], v[12:15], v[52:55]
	v_mfma_f32_16x16x32_bf16 v[56:59], v[36:39], v[12:15], v[56:59]
	v_mfma_f32_16x16x32_bf16 v[48:51], v[80:83], v[12:15], v[48:51]
	v_mfma_f32_16x16x32_bf16 v[8:11], v[4:7], v[28:31], v[8:11]
	v_mfma_f32_16x16x32_bf16 v[44:47], v[24:27], v[28:31], v[44:47]
	v_mfma_f32_16x16x32_bf16 v[64:67], v[36:39], v[28:31], v[64:67]
	v_mfma_f32_16x16x32_bf16 v[76:79], v[80:83], v[28:31], v[76:79]
	v_mfma_f32_16x16x32_bf16 v[108:111], v[4:7], v[40:43], v[108:111]
	v_mfma_f32_16x16x32_bf16 v[116:119], v[24:27], v[40:43], v[116:119]
	v_mfma_f32_16x16x32_bf16 v[124:127], v[36:39], v[40:43], v[124:127]
	v_mfma_f32_16x16x32_bf16 v[128:131], v[80:83], v[40:43], v[128:131]
	v_mfma_f32_16x16x32_bf16 v[20:23], v[84:87], v[88:91], v[20:23]
	v_mfma_f32_16x16x32_bf16 v[72:75], v[96:99], v[88:91], v[72:75]
	v_mfma_f32_16x16x32_bf16 v[68:71], v[104:107], v[88:91], v[68:71]
	v_mfma_f32_16x16x32_bf16 v[60:63], v[120:123], v[88:91], v[60:63]
	v_mfma_f32_16x16x32_bf16 v[16:19], v[84:87], v[92:95], v[16:19]
	v_mfma_f32_16x16x32_bf16 v[52:55], v[96:99], v[92:95], v[52:55]
	v_mfma_f32_16x16x32_bf16 v[56:59], v[104:107], v[92:95], v[56:59]
	v_mfma_f32_16x16x32_bf16 v[48:51], v[120:123], v[92:95], v[48:51]
	v_mfma_f32_16x16x32_bf16 v[8:11], v[84:87], v[100:103], v[8:11]
	v_mfma_f32_16x16x32_bf16 v[44:47], v[96:99], v[100:103], v[44:47]
	v_mfma_f32_16x16x32_bf16 v[64:67], v[104:107], v[100:103], v[64:67]
	v_mfma_f32_16x16x32_bf16 v[76:79], v[120:123], v[100:103], v[76:79]
	v_mfma_f32_16x16x32_bf16 v[108:111], v[84:87], v[112:115], v[108:111]
	v_mfma_f32_16x16x32_bf16 v[116:119], v[96:99], v[112:115], v[116:119]
	v_mfma_f32_16x16x32_bf16 v[124:127], v[104:107], v[112:115], v[124:127]
	v_mfma_f32_16x16x32_bf16 v[128:131], v[120:123], v[112:115], v[128:131]
	global_load_dwordx4 v[0:3], v132, s[0:1] offset:512
	global_load_dwordx4 v[88:91], v132, s[0:1] offset:576
	global_load_dwordx4 v[4:7], v132, s[4:5] offset:512
	global_load_dwordx4 v[84:87], v132, s[4:5] offset:576
	global_load_dwordx4 v[12:15], v138, s[0:1] offset:512
	global_load_dwordx4 v[92:95], v138, s[0:1] offset:576
	global_load_dwordx4 v[24:27], v138, s[4:5] offset:512
	global_load_dwordx4 v[96:99], v138, s[4:5] offset:576
	global_load_dwordx4 v[28:31], v136, s[0:1] offset:512
	global_load_dwordx4 v[100:103], v136, s[0:1] offset:576
	global_load_dwordx4 v[36:39], v136, s[4:5] offset:512
	global_load_dwordx4 v[104:107], v136, s[4:5] offset:576
	global_load_dwordx4 v[40:43], v134, s[0:1] offset:512
	global_load_dwordx4 v[112:115], v134, s[0:1] offset:576
	global_load_dwordx4 v[80:83], v134, s[4:5] offset:512
	global_load_dwordx4 v[120:123], v134, s[4:5] offset:576
	s_waitcnt vmcnt(16)
; #define SK_LD(bu, PA, PB) do { _Pragma("unroll") for (int k_ = 0; k_ < 2; ++k_) _Pragma("unroll") for (int i_ = 0; i_ < 4; ++i_) { fa[bu][k_][i_] = *(const bf16x8*)((PA) + va[i_] + k_ * 64); fb[bu][k_][i_] = *(const bf16x8*)((PB) + vb[i_] + k_ * 64); } } while (0)
; #define SK_MM(bu) do { _Pragma("unroll") for (int k_ = 0; k_ < 2; ++k_) _Pragma("unroll") for (int m_ = 0; m_ < 4; ++m_) _Pragma("unroll") for (int n_ = 0; n_ < 4; ++n_) acc[m_][n_] = mfma16(fb[bu][k_][n_], fa[bu][k_][m_], acc[m_][n_]); } while (0)
; __device__ __forceinline__ void skinny_kloop(f32x4 (&acc)[4][4], const char* pa, const char* pb, const unsigned (&va)[4], const unsigned (&vb)[4], const int nc) {
;     bf16x8 fa[2][2][4], fb[2][2][4];
;     ...
;     SK_LD(0, pa, pb);
; #pragma unroll 1
;     for (int c = 0; c < nc; c += 2) {
;         const int o1 = (c + 1 < nc) ? 128 : 0, o2 = (c + 2 < nc) ? 256 : 0;
;         SK_LD(1, pa + o1, pb + o1);
;         SK_MM(0);
;         SK_LD(0, pa + o2, pb + o2);
;         if (c + 1 < nc) SK_MM(1);
;         pa += 256; pb += 256;
;     }
	v_mfma_f32_16x16x32_bf16 v[20:23], v[156:159], v[140:143], v[20:23]
	v_mfma_f32_16x16x32_bf16 v[72:75], v[160:163], v[140:143], v[72:75]
	v_mfma_f32_16x16x32_bf16 v[68:71], v[164:167], v[140:143], v[68:71]
	v_mfma_f32_16x16x32_bf16 v[60:63], v[168:171], v[140:143], v[60:63]
	v_mfma_f32_16x16x32_bf16 v[16:19], v[156:159], v[144:147], v[16:19]
	v_mfma_f32_16x16x32_bf16 v[52:55], v[160:163], v[144:147], v[52:55]
	v_mfma_f32_16x16x32_bf16 v[56:59], v[164:167], v[144:147], v[56:59]
	v_mfma_f32_16x16x32_bf16 v[48:51], v[168:171], v[144:147], v[48:51]
	v_mfma_f32_16x16x32_bf16 v[8:11], v[156:159], v[148:151], v[8:11]
	v_mfma_f32_16x16x32_bf16 v[44:47], v[160:163], v[148:151], v[44:47]
	v_mfma_f32_16x16x32_bf16 v[64:67], v[164:167], v[148:151], v[64:67]
	v_mfma_f32_16x16x32_bf16 v[76:79], v[168:171], v[148:151], v[76:79]
	v_mfma_f32_16x16x32_bf16 v[108:111], v[156:159], v[152:155], v[108:111]
	v_mfma_f32_16x16x32_bf16 v[116:119], v[160:163], v[152:155], v[116:119]
	v_mfma_f32_16x16x32_bf16 v[124:127], v[164:167], v[152:155], v[124:127]
	v_mfma_f32_16x16x32_bf16 v[128:131], v[168:171], v[152:155], v[128:131]
	v_mfma_f32_16x16x32_bf16 v[20:23], v[204:207], v[172:175], v[20:23]
	v_mfma_f32_16x16x32_bf16 v[72:75], v[208:211], v[172:175], v[72:75]
	v_mfma_f32_16x16x32_bf16 v[68:71], v[212:215], v[172:175], v[68:71]
	v_mfma_f32_16x16x32_bf16 v[60:63], v[216:219], v[172:175], v[60:63]
	v_mfma_f32_16x16x32_bf16 v[16:19], v[204:207], v[192:195], v[16:19]
	v_mfma_f32_16x16x32_bf16 v[52:55], v[208:211], v[192:195], v[52:55]
	v_mfma_f32_16x16x32_bf16 v[56:59], v[212:215], v[192:195], v[56:59]
	v_mfma_f32_16x16x32_bf16 v[48:51], v[216:219], v[192:195], v[48:51]
	v_mfma_f32_16x16x32_bf16 v[8:11], v[204:207], v[196:199], v[8:11]
	v_mfma_f32_16x16x32_bf16 v[44:47], v[208:211], v[196:199], v[44:47]
	v_mfma_f32_16x16x32_bf16 v[64:67], v[212:215], v[196:199], v[64:67]
	v_mfma_f32_16x16x32_bf16 v[76:79], v[216:219], v[196:199], v[76:79]
	v_mfma_f32_16x16x32_bf16 v[108:111], v[204:207], v[200:203], v[108:111]
	v_mfma_f32_16x16x32_bf16 v[116:119], v[208:211], v[200:203], v[116:119]
	v_mfma_f32_16x16x32_bf16 v[124:127], v[212:215], v[200:203], v[124:127]
	v_mfma_f32_16x16x32_bf16 v[128:131], v[216:219], v[200:203], v[128:131]
	global_load_dwordx4 v[140:143], v132, s[0:1] offset:640
	global_load_dwordx4 v[172:175], v132, s[0:1] offset:704
	global_load_dwordx4 v[156:159], v132, s[4:5] offset:640
	global_load_dwordx4 v[204:207], v132, s[4:5] offset:704
	global_load_dwordx4 v[144:147], v138, s[0:1] offset:640
	global_load_dwordx4 v[192:195], v138, s[0:1] offset:704
	global_load_dwordx4 v[160:163], v138, s[4:5] offset:640
	global_load_dwordx4 v[208:211], v138, s[4:5] offset:704
	global_load_dwordx4 v[148:151], v136, s[0:1] offset:640
	global_load_dwordx4 v[196:199], v136, s[0:1] offset:704
	global_load_dwordx4 v[164:167], v136, s[4:5] offset:640
	global_load_dwordx4 v[212:215], v136, s[4:5] offset:704
	global_load_dwordx4 v[152:155], v134, s[0:1] offset:640
	global_load_dwordx4 v[200:203], v134, s[0:1] offset:704
	global_load_dwordx4 v[168:171], v134, s[4:5] offset:640
	global_load_dwordx4 v[216:219], v134, s[4:5] offset:704
	s_waitcnt vmcnt(16)
	v_mfma_f32_16x16x32_bf16 v[20:23], v[4:7], v[0:3], v[20:23]
	v_mfma_f32_16x16x32_bf16 v[72:75], v[24:27], v[0:3], v[72:75]
	v_mfma_f32_16x16x32_bf16 v[68:71], v[36:39], v[0:3], v[68:71]
	v_mfma_f32_16x16x32_bf16 v[60:63], v[80:83], v[0:3], v[60:63]
	v_mfma_f32_16x16x32_bf16 v[16:19], v[4:7], v[12:15], v[16:19]
	v_mfma_f32_16x16x32_bf16 v[52:55], v[24:27], v[12:15], v[52:55]
	v_mfma_f32_16x16x32_bf16 v[56:59], v[36:39], v[12:15], v[56:59]
	v_mfma_f32_16x16x32_bf16 v[48:51], v[80:83], v[12:15], v[48:51]
	v_mfma_f32_16x16x32_bf16 v[8:11], v[4:7], v[28:31], v[8:11]
	v_mfma_f32_16x16x32_bf16 v[44:47], v[24:27], v[28:31], v[44:47]
	v_mfma_f32_16x16x32_bf16 v[64:67], v[36:39], v[28:31], v[64:67]
	v_mfma_f32_16x16x32_bf16 v[76:79], v[80:83], v[28:31], v[76:79]
	v_mfma_f32_16x16x32_bf16 v[108:111], v[4:7], v[40:43], v[108:111]
	v_mfma_f32_16x16x32_bf16 v[116:119], v[24:27], v[40:43], v[116:119]
	v_mfma_f32_16x16x32_bf16 v[124:127], v[36:39], v[40:43], v[124:127]
	v_mfma_f32_16x16x32_bf16 v[128:131], v[80:83], v[40:43], v[128:131]
	v_mfma_f32_16x16x32_bf16 v[20:23], v[84:87], v[88:91], v[20:23]
	v_mfma_f32_16x16x32_bf16 v[72:75], v[96:99], v[88:91], v[72:75]
	v_mfma_f32_16x16x32_bf16 v[68:71], v[104:107], v[88:91], v[68:71]
	v_mfma_f32_16x16x32_bf16 v[60:63], v[120:123], v[88:91], v[60:63]
	v_mfma_f32_16x16x32_bf16 v[16:19], v[84:87], v[92:95], v[16:19]
	v_mfma_f32_16x16x32_bf16 v[52:55], v[96:99], v[92:95], v[52:55]
	v_mfma_f32_16x16x32_bf16 v[56:59], v[104:107], v[92:95], v[56:59]
	v_mfma_f32_16x16x32_bf16 v[48:51], v[120:123], v[92:95], v[48:51]
	v_mfma_f32_16x16x32_bf16 v[8:11], v[84:87], v[100:103], v[8:11]
	v_mfma_f32_16x16x32_bf16 v[44:47], v[96:99], v[100:103], v[44:47]
	v_mfma_f32_16x16x32_bf16 v[64:67], v[104:107], v[100:103], v[64:67]
	v_mfma_f32_16x16x32_bf16 v[76:79], v[120:123], v[100:103], v[76:79]
	v_mfma_f32_16x16x32_bf16 v[108:111], v[84:87], v[112:115], v[108:111]
	v_mfma_f32_16x16x32_bf16 v[116:119], v[96:99], v[112:115], v[116:119]
	v_mfma_f32_16x16x32_bf16 v[124:127], v[104:107], v[112:115], v[124:127]
	v_mfma_f32_16x16x32_bf16 v[128:131], v[120:123], v[112:115], v[128:131]
	global_load_dwordx4 v[0:3], v132, s[0:1] offset:768
	global_load_dwordx4 v[88:91], v132, s[0:1] offset:832
	global_load_dwordx4 v[4:7], v132, s[4:5] offset:768
	global_load_dwordx4 v[84:87], v132, s[4:5] offset:832
	global_load_dwordx4 v[12:15], v138, s[0:1] offset:768
	global_load_dwordx4 v[92:95], v138, s[0:1] offset:832
	global_load_dwordx4 v[24:27], v138, s[4:5] offset:768
	global_load_dwordx4 v[96:99], v138, s[4:5] offset:832
	global_load_dwordx4 v[28:31], v136, s[0:1] offset:768
	global_load_dwordx4 v[100:103], v136, s[0:1] offset:832
	global_load_dwordx4 v[36:39], v136, s[4:5] offset:768
	global_load_dwordx4 v[104:107], v136, s[4:5] offset:832
	global_load_dwordx4 v[40:43], v134, s[0:1] offset:768
	global_load_dwordx4 v[112:115], v134, s[0:1] offset:832
	global_load_dwordx4 v[80:83], v134, s[4:5] offset:768
	global_load_dwordx4 v[120:123], v134, s[4:5] offset:832
	s_waitcnt vmcnt(16)
; #define SK_LD(bu, PA, PB) do { _Pragma("unroll") for (int k_ = 0; k_ < 2; ++k_) _Pragma("unroll") for (int i_ = 0; i_ < 4; ++i_) { fa[bu][k_][i_] = *(const bf16x8*)((PA) + va[i_] + k_ * 64); fb[bu][k_][i_] = *(const bf16x8*)((PB) + vb[i_] + k_ * 64); } } while (0)
; #define SK_MM(bu) do { _Pragma("unroll") for (int k_ = 0; k_ < 2; ++k_) _Pragma("unroll") for (int m_ = 0; m_ < 4; ++m_) _Pragma("unroll") for (int n_ = 0; n_ < 4; ++n_) acc[m_][n_] = mfma16(fb[bu][k_][n_], fa[bu][k_][m_], acc[m_][n_]); } while (0)
; __device__ __forceinline__ void skinny_kloop(f32x4 (&acc)[4][4], const char* pa, const char* pb, const unsigned (&va)[4], const unsigned (&vb)[4], const int nc) {
;     bf16x8 fa[2][2][4], fb[2][2][4];
;     ...
;     SK_LD(0, pa, pb);
; #pragma unroll 1
;     for (int c = 0; c < nc; c += 2) {
;         const int o1 = (c + 1 < nc) ? 128 : 0, o2 = (c + 2 < nc) ? 256 : 0;
;         SK_LD(1, pa + o1, pb + o1);
;         SK_MM(0);
;         SK_LD(0, pa + o2, pb + o2);
;         if (c + 1 < nc) SK_MM(1);
;         pa += 256; pb += 256;
;     }
	v_mfma_f32_16x16x32_bf16 v[20:23], v[156:159], v[140:143], v[20:23]
	v_mfma_f32_16x16x32_bf16 v[72:75], v[160:163], v[140:143], v[72:75]
	v_mfma_f32_16x16x32_bf16 v[68:71], v[164:167], v[140:143], v[68:71]
	v_mfma_f32_16x16x32_bf16 v[60:63], v[168:171], v[140:143], v[60:63]
	v_mfma_f32_16x16x32_bf16 v[16:19], v[156:159], v[144:147], v[16:19]
	v_mfma_f32_16x16x32_bf16 v[52:55], v[160:163], v[144:147], v[52:55]
	v_mfma_f32_16x16x32_bf16 v[56:59], v[164:167], v[144:147], v[56:59]
	v_mfma_f32_16x16x32_bf16 v[48:51], v[168:171], v[144:147], v[48:51]
	v_mfma_f32_16x16x32_bf16 v[8:11], v[156:159], v[148:151], v[8:11]
	v_mfma_f32_16x16x32_bf16 v[44:47], v[160:163], v[148:151], v[44:47]
	v_mfma_f32_16x16x32_bf16 v[64:67], v[164:167], v[148:151], v[64:67]
	v_mfma_f32_16x16x32_bf16 v[76:79], v[168:171], v[148:151], v[76:79]
	v_mfma_f32_16x16x32_bf16 v[108:111], v[156:159], v[152:155], v[108:111]
	v_mfma_f32_16x16x32_bf16 v[116:119], v[160:163], v[152:155], v[116:119]
	v_mfma_f32_16x16x32_bf16 v[124:127], v[164:167], v[152:155], v[124:127]
	v_mfma_f32_16x16x32_bf16 v[128:131], v[168:171], v[152:155], v[128:131]
	v_mfma_f32_16x16x32_bf16 v[20:23], v[204:207], v[172:175], v[20:23]
	v_mfma_f32_16x16x32_bf16 v[72:75], v[208:211], v[172:175], v[72:75]
	v_mfma_f32_16x16x32_bf16 v[68:71], v[212:215], v[172:175], v[68:71]
	v_mfma_f32_16x16x32_bf16 v[60:63], v[216:219], v[172:175], v[60:63]
	v_mfma_f32_16x16x32_bf16 v[16:19], v[204:207], v[192:195], v[16:19]
	v_mfma_f32_16x16x32_bf16 v[52:55], v[208:211], v[192:195], v[52:55]
	v_mfma_f32_16x16x32_bf16 v[56:59], v[212:215], v[192:195], v[56:59]
	v_mfma_f32_16x16x32_bf16 v[48:51], v[216:219], v[192:195], v[48:51]
	v_mfma_f32_16x16x32_bf16 v[8:11], v[204:207], v[196:199], v[8:11]
	v_mfma_f32_16x16x32_bf16 v[44:47], v[208:211], v[196:199], v[44:47]
	v_mfma_f32_16x16x32_bf16 v[64:67], v[212:215], v[196:199], v[64:67]
	v_mfma_f32_16x16x32_bf16 v[76:79], v[216:219], v[196:199], v[76:79]
	v_mfma_f32_16x16x32_bf16 v[108:111], v[204:207], v[200:203], v[108:111]
	v_mfma_f32_16x16x32_bf16 v[116:119], v[208:211], v[200:203], v[116:119]
	v_mfma_f32_16x16x32_bf16 v[124:127], v[212:215], v[200:203], v[124:127]
	v_mfma_f32_16x16x32_bf16 v[128:131], v[216:219], v[200:203], v[128:131]
	global_load_dwordx4 v[140:143], v132, s[0:1] offset:896
	global_load_dwordx4 v[172:175], v132, s[0:1] offset:960
	global_load_dwordx4 v[156:159], v132, s[4:5] offset:896
	global_load_dwordx4 v[204:207], v132, s[4:5] offset:960
	global_load_dwordx4 v[144:147], v138, s[0:1] offset:896
	global_load_dwordx4 v[192:195], v138, s[0:1] offset:960
	global_load_dwordx4 v[160:163], v138, s[4:5] offset:896
	global_load_dwordx4 v[208:211], v138, s[4:5] offset:960
	global_load_dwordx4 v[148:151], v136, s[0:1] offset:896
	global_load_dwordx4 v[196:199], v136, s[0:1] offset:960
	global_load_dwordx4 v[164:167], v136, s[4:5] offset:896
	global_load_dwordx4 v[212:215], v136, s[4:5] offset:960
	global_load_dwordx4 v[152:155], v134, s[0:1] offset:896
	global_load_dwordx4 v[200:203], v134, s[0:1] offset:960
	global_load_dwordx4 v[168:171], v134, s[4:5] offset:896
	global_load_dwordx4 v[216:219], v134, s[4:5] offset:960
	s_waitcnt vmcnt(16)
	v_mfma_f32_16x16x32_bf16 v[20:23], v[4:7], v[0:3], v[20:23]
	v_mfma_f32_16x16x32_bf16 v[72:75], v[24:27], v[0:3], v[72:75]
	v_mfma_f32_16x16x32_bf16 v[68:71], v[36:39], v[0:3], v[68:71]
	v_mfma_f32_16x16x32_bf16 v[60:63], v[80:83], v[0:3], v[60:63]
	v_mfma_f32_16x16x32_bf16 v[16:19], v[4:7], v[12:15], v[16:19]
	v_mfma_f32_16x16x32_bf16 v[52:55], v[24:27], v[12:15], v[52:55]
	v_mfma_f32_16x16x32_bf16 v[56:59], v[36:39], v[12:15], v[56:59]
	v_mfma_f32_16x16x32_bf16 v[48:51], v[80:83], v[12:15], v[48:51]
	v_mfma_f32_16x16x32_bf16 v[8:11], v[4:7], v[28:31], v[8:11]
	v_mfma_f32_16x16x32_bf16 v[44:47], v[24:27], v[28:31], v[44:47]
	v_mfma_f32_16x16x32_bf16 v[64:67], v[36:39], v[28:31], v[64:67]
	v_mfma_f32_16x16x32_bf16 v[76:79], v[80:83], v[28:31], v[76:79]
	v_mfma_f32_16x16x32_bf16 v[108:111], v[4:7], v[40:43], v[108:111]
	v_mfma_f32_16x16x32_bf16 v[116:119], v[24:27], v[40:43], v[116:119]
	v_mfma_f32_16x16x32_bf16 v[124:127], v[36:39], v[40:43], v[124:127]
	v_mfma_f32_16x16x32_bf16 v[128:131], v[80:83], v[40:43], v[128:131]
	v_mfma_f32_16x16x32_bf16 v[20:23], v[84:87], v[88:91], v[20:23]
	v_mfma_f32_16x16x32_bf16 v[72:75], v[96:99], v[88:91], v[72:75]
	v_mfma_f32_16x16x32_bf16 v[68:71], v[104:107], v[88:91], v[68:71]
	v_mfma_f32_16x16x32_bf16 v[60:63], v[120:123], v[88:91], v[60:63]
	v_mfma_f32_16x16x32_bf16 v[16:19], v[84:87], v[92:95], v[16:19]
	v_mfma_f32_16x16x32_bf16 v[52:55], v[96:99], v[92:95], v[52:55]
	v_mfma_f32_16x16x32_bf16 v[56:59], v[104:107], v[92:95], v[56:59]
	v_mfma_f32_16x16x32_bf16 v[48:51], v[120:123], v[92:95], v[48:51]
	v_mfma_f32_16x16x32_bf16 v[8:11], v[84:87], v[100:103], v[8:11]
	v_mfma_f32_16x16x32_bf16 v[44:47], v[96:99], v[100:103], v[44:47]
	v_mfma_f32_16x16x32_bf16 v[64:67], v[104:107], v[100:103], v[64:67]
	v_mfma_f32_16x16x32_bf16 v[76:79], v[120:123], v[100:103], v[76:79]
	v_mfma_f32_16x16x32_bf16 v[108:111], v[84:87], v[112:115], v[108:111]
	v_mfma_f32_16x16x32_bf16 v[116:119], v[96:99], v[112:115], v[116:119]
	v_mfma_f32_16x16x32_bf16 v[124:127], v[104:107], v[112:115], v[124:127]
	v_mfma_f32_16x16x32_bf16 v[128:131], v[120:123], v[112:115], v[128:131]
	global_load_dwordx4 v[0:3], v132, s[0:1] offset:1024
	global_load_dwordx4 v[88:91], v132, s[0:1] offset:1088
	global_load_dwordx4 v[4:7], v132, s[4:5] offset:1024
	global_load_dwordx4 v[84:87], v132, s[4:5] offset:1088
	global_load_dwordx4 v[12:15], v138, s[0:1] offset:1024
	global_load_dwordx4 v[92:95], v138, s[0:1] offset:1088
	global_load_dwordx4 v[24:27], v138, s[4:5] offset:1024
	global_load_dwordx4 v[96:99], v138, s[4:5] offset:1088
	global_load_dwordx4 v[28:31], v136, s[0:1] offset:1024
	global_load_dwordx4 v[100:103], v136, s[0:1] offset:1088
	global_load_dwordx4 v[36:39], v136, s[4:5] offset:1024
	global_load_dwordx4 v[104:107], v136, s[4:5] offset:1088
	global_load_dwordx4 v[40:43], v134, s[0:1] offset:1024
	global_load_dwordx4 v[112:115], v134, s[0:1] offset:1088
	global_load_dwordx4 v[80:83], v134, s[4:5] offset:1024
	global_load_dwordx4 v[120:123], v134, s[4:5] offset:1088
	s_waitcnt vmcnt(16)
; #define SK_LD(bu, PA, PB) do { _Pragma("unroll") for (int k_ = 0; k_ < 2; ++k_) _Pragma("unroll") for (int i_ = 0; i_ < 4; ++i_) { fa[bu][k_][i_] = *(const bf16x8*)((PA) + va[i_] + k_ * 64); fb[bu][k_][i_] = *(const bf16x8*)((PB) + vb[i_] + k_ * 64); } } while (0)
; #define SK_MM(bu) do { _Pragma("unroll") for (int k_ = 0; k_ < 2; ++k_) _Pragma("unroll") for (int m_ = 0; m_ < 4; ++m_) _Pragma("unroll") for (int n_ = 0; n_ < 4; ++n_) acc[m_][n_] = mfma16(fb[bu][k_][n_], fa[bu][k_][m_], acc[m_][n_]); } while (0)
; __device__ __forceinline__ void skinny_kloop(f32x4 (&acc)[4][4], const char* pa, const char* pb, const unsigned (&va)[4], const unsigned (&vb)[4], const int nc) {
;     bf16x8 fa[2][2][4], fb[2][2][4];
;     ...
;     SK_LD(0, pa, pb);
; #pragma unroll 1
;     for (int c = 0; c < nc; c += 2) {
;         const int o1 = (c + 1 < nc) ? 128 : 0, o2 = (c + 2 < nc) ? 256 : 0;
;         SK_LD(1, pa + o1, pb + o1);
;         SK_MM(0);
;         SK_LD(0, pa + o2, pb + o2);
;         if (c + 1 < nc) SK_MM(1);
;         pa += 256; pb += 256;
;     }
	v_mfma_f32_16x16x32_bf16 v[20:23], v[156:159], v[140:143], v[20:23]
	v_mfma_f32_16x16x32_bf16 v[72:75], v[160:163], v[140:143], v[72:75]
	v_mfma_f32_16x16x32_bf16 v[68:71], v[164:167], v[140:143], v[68:71]
	v_mfma_f32_16x16x32_bf16 v[60:63], v[168:171], v[140:143], v[60:63]
	v_mfma_f32_16x16x32_bf16 v[16:19], v[156:159], v[144:147], v[16:19]
	v_mfma_f32_16x16x32_bf16 v[52:55], v[160:163], v[144:147], v[52:55]
	v_mfma_f32_16x16x32_bf16 v[56:59], v[164:167], v[144:147], v[56:59]
	v_mfma_f32_16x16x32_bf16 v[48:51], v[168:171], v[144:147], v[48:51]
	v_mfma_f32_16x16x32_bf16 v[8:11], v[156:159], v[148:151], v[8:11]
	v_mfma_f32_16x16x32_bf16 v[44:47], v[160:163], v[148:151], v[44:47]
	v_mfma_f32_16x16x32_bf16 v[64:67], v[164:167], v[148:151], v[64:67]
	v_mfma_f32_16x16x32_bf16 v[76:79], v[168:171], v[148:151], v[76:79]
	v_mfma_f32_16x16x32_bf16 v[108:111], v[156:159], v[152:155], v[108:111]
	v_mfma_f32_16x16x32_bf16 v[116:119], v[160:163], v[152:155], v[116:119]
	v_mfma_f32_16x16x32_bf16 v[124:127], v[164:167], v[152:155], v[124:127]
	v_mfma_f32_16x16x32_bf16 v[128:131], v[168:171], v[152:155], v[128:131]
	v_mfma_f32_16x16x32_bf16 v[20:23], v[204:207], v[172:175], v[20:23]
	v_mfma_f32_16x16x32_bf16 v[72:75], v[208:211], v[172:175], v[72:75]
	v_mfma_f32_16x16x32_bf16 v[68:71], v[212:215], v[172:175], v[68:71]
	v_mfma_f32_16x16x32_bf16 v[60:63], v[216:219], v[172:175], v[60:63]
	v_mfma_f32_16x16x32_bf16 v[16:19], v[204:207], v[192:195], v[16:19]
	v_mfma_f32_16x16x32_bf16 v[52:55], v[208:211], v[192:195], v[52:55]
	v_mfma_f32_16x16x32_bf16 v[56:59], v[212:215], v[192:195], v[56:59]
	v_mfma_f32_16x16x32_bf16 v[48:51], v[216:219], v[192:195], v[48:51]
	v_mfma_f32_16x16x32_bf16 v[8:11], v[204:207], v[196:199], v[8:11]
	v_mfma_f32_16x16x32_bf16 v[44:47], v[208:211], v[196:199], v[44:47]
	v_mfma_f32_16x16x32_bf16 v[64:67], v[212:215], v[196:199], v[64:67]
	v_mfma_f32_16x16x32_bf16 v[76:79], v[216:219], v[196:199], v[76:79]
	v_mfma_f32_16x16x32_bf16 v[108:111], v[204:207], v[200:203], v[108:111]
	v_mfma_f32_16x16x32_bf16 v[116:119], v[208:211], v[200:203], v[116:119]
	v_mfma_f32_16x16x32_bf16 v[124:127], v[212:215], v[200:203], v[124:127]
	v_mfma_f32_16x16x32_bf16 v[128:131], v[216:219], v[200:203], v[128:131]
	global_load_dwordx4 v[140:143], v132, s[0:1] offset:1152
	global_load_dwordx4 v[172:175], v132, s[0:1] offset:1216
	global_load_dwordx4 v[156:159], v132, s[4:5] offset:1152
	global_load_dwordx4 v[204:207], v132, s[4:5] offset:1216
	global_load_dwordx4 v[144:147], v138, s[0:1] offset:1152
	global_load_dwordx4 v[192:195], v138, s[0:1] offset:1216
	global_load_dwordx4 v[160:163], v138, s[4:5] offset:1152
	global_load_dwordx4 v[208:211], v138, s[4:5] offset:1216
	global_load_dwordx4 v[148:151], v136, s[0:1] offset:1152
	global_load_dwordx4 v[196:199], v136, s[0:1] offset:1216
	global_load_dwordx4 v[164:167], v136, s[4:5] offset:1152
	global_load_dwordx4 v[212:215], v136, s[4:5] offset:1216
	global_load_dwordx4 v[152:155], v134, s[0:1] offset:1152
	global_load_dwordx4 v[200:203], v134, s[0:1] offset:1216
	global_load_dwordx4 v[168:171], v134, s[4:5] offset:1152
	global_load_dwordx4 v[216:219], v134, s[4:5] offset:1216
	s_waitcnt vmcnt(16)
	v_mfma_f32_16x16x32_bf16 v[20:23], v[4:7], v[0:3], v[20:23]
	v_mfma_f32_16x16x32_bf16 v[72:75], v[24:27], v[0:3], v[72:75]
	v_mfma_f32_16x16x32_bf16 v[68:71], v[36:39], v[0:3], v[68:71]
	v_mfma_f32_16x16x32_bf16 v[60:63], v[80:83], v[0:3], v[60:63]
	v_mfma_f32_16x16x32_bf16 v[16:19], v[4:7], v[12:15], v[16:19]
	v_mfma_f32_16x16x32_bf16 v[52:55], v[24:27], v[12:15], v[52:55]
	v_mfma_f32_16x16x32_bf16 v[56:59], v[36:39], v[12:15], v[56:59]
	v_mfma_f32_16x16x32_bf16 v[48:51], v[80:83], v[12:15], v[48:51]
	v_mfma_f32_16x16x32_bf16 v[8:11], v[4:7], v[28:31], v[8:11]
	v_mfma_f32_16x16x32_bf16 v[44:47], v[24:27], v[28:31], v[44:47]
	v_mfma_f32_16x16x32_bf16 v[64:67], v[36:39], v[28:31], v[64:67]
	v_mfma_f32_16x16x32_bf16 v[76:79], v[80:83], v[28:31], v[76:79]
	v_mfma_f32_16x16x32_bf16 v[108:111], v[4:7], v[40:43], v[108:111]
	v_mfma_f32_16x16x32_bf16 v[116:119], v[24:27], v[40:43], v[116:119]
	v_mfma_f32_16x16x32_bf16 v[124:127], v[36:39], v[40:43], v[124:127]
	v_mfma_f32_16x16x32_bf16 v[128:131], v[80:83], v[40:43], v[128:131]
	v_mfma_f32_16x16x32_bf16 v[20:23], v[84:87], v[88:91], v[20:23]
	v_mfma_f32_16x16x32_bf16 v[72:75], v[96:99], v[88:91], v[72:75]
	v_mfma_f32_16x16x32_bf16 v[68:71], v[104:107], v[88:91], v[68:71]
	v_mfma_f32_16x16x32_bf16 v[60:63], v[120:123], v[88:91], v[60:63]
	v_mfma_f32_16x16x32_bf16 v[16:19], v[84:87], v[92:95], v[16:19]
	v_mfma_f32_16x16x32_bf16 v[52:55], v[96:99], v[92:95], v[52:55]
	v_mfma_f32_16x16x32_bf16 v[56:59], v[104:107], v[92:95], v[56:59]
	v_mfma_f32_16x16x32_bf16 v[48:51], v[120:123], v[92:95], v[48:51]
	v_mfma_f32_16x16x32_bf16 v[8:11], v[84:87], v[100:103], v[8:11]
	v_mfma_f32_16x16x32_bf16 v[44:47], v[96:99], v[100:103], v[44:47]
	v_mfma_f32_16x16x32_bf16 v[64:67], v[104:107], v[100:103], v[64:67]
	v_mfma_f32_16x16x32_bf16 v[76:79], v[120:123], v[100:103], v[76:79]
	v_mfma_f32_16x16x32_bf16 v[108:111], v[84:87], v[112:115], v[108:111]
	v_mfma_f32_16x16x32_bf16 v[116:119], v[96:99], v[112:115], v[116:119]
	v_mfma_f32_16x16x32_bf16 v[124:127], v[104:107], v[112:115], v[124:127]
	v_mfma_f32_16x16x32_bf16 v[128:131], v[120:123], v[112:115], v[128:131]
	global_load_dwordx4 v[0:3], v132, s[0:1] offset:1280
	global_load_dwordx4 v[88:91], v132, s[0:1] offset:1344
	global_load_dwordx4 v[4:7], v132, s[4:5] offset:1280
	global_load_dwordx4 v[84:87], v132, s[4:5] offset:1344
	global_load_dwordx4 v[12:15], v138, s[0:1] offset:1280
	global_load_dwordx4 v[92:95], v138, s[0:1] offset:1344
	global_load_dwordx4 v[24:27], v138, s[4:5] offset:1280
	global_load_dwordx4 v[96:99], v138, s[4:5] offset:1344
	global_load_dwordx4 v[28:31], v136, s[0:1] offset:1280
	global_load_dwordx4 v[100:103], v136, s[0:1] offset:1344
	global_load_dwordx4 v[36:39], v136, s[4:5] offset:1280
	global_load_dwordx4 v[104:107], v136, s[4:5] offset:1344
	global_load_dwordx4 v[40:43], v134, s[0:1] offset:1280
	global_load_dwordx4 v[112:115], v134, s[0:1] offset:1344
	global_load_dwordx4 v[80:83], v134, s[4:5] offset:1280
	global_load_dwordx4 v[120:123], v134, s[4:5] offset:1344
	s_waitcnt vmcnt(16)
; #define SK_LD(bu, PA, PB) do { _Pragma("unroll") for (int k_ = 0; k_ < 2; ++k_) _Pragma("unroll") for (int i_ = 0; i_ < 4; ++i_) { fa[bu][k_][i_] = *(const bf16x8*)((PA) + va[i_] + k_ * 64); fb[bu][k_][i_] = *(const bf16x8*)((PB) + vb[i_] + k_ * 64); } } while (0)
; #define SK_MM(bu) do { _Pragma("unroll") for (int k_ = 0; k_ < 2; ++k_) _Pragma("unroll") for (int m_ = 0; m_ < 4; ++m_) _Pragma("unroll") for (int n_ = 0; n_ < 4; ++n_) acc[m_][n_] = mfma16(fb[bu][k_][n_], fa[bu][k_][m_], acc[m_][n_]); } while (0)
; __device__ __forceinline__ void skinny_kloop(f32x4 (&acc)[4][4], const char* pa, const char* pb, const unsigned (&va)[4], const unsigned (&vb)[4], const int nc) {
;     bf16x8 fa[2][2][4], fb[2][2][4];
;     ...
;     SK_LD(0, pa, pb);
; #pragma unroll 1
;     for (int c = 0; c < nc; c += 2) {
;         const int o1 = (c + 1 < nc) ? 128 : 0, o2 = (c + 2 < nc) ? 256 : 0;
;         SK_LD(1, pa + o1, pb + o1);
;         SK_MM(0);
;         SK_LD(0, pa + o2, pb + o2);
;         if (c + 1 < nc) SK_MM(1);
;         pa += 256; pb += 256;
;     }
	v_mfma_f32_16x16x32_bf16 v[20:23], v[156:159], v[140:143], v[20:23]
	v_mfma_f32_16x16x32_bf16 v[72:75], v[160:163], v[140:143], v[72:75]
	v_mfma_f32_16x16x32_bf16 v[68:71], v[164:167], v[140:143], v[68:71]
	v_mfma_f32_16x16x32_bf16 v[60:63], v[168:171], v[140:143], v[60:63]
	v_mfma_f32_16x16x32_bf16 v[16:19], v[156:159], v[144:147], v[16:19]
	v_mfma_f32_16x16x32_bf16 v[52:55], v[160:163], v[144:147], v[52:55]
	v_mfma_f32_16x16x32_bf16 v[56:59], v[164:167], v[144:147], v[56:59]
	v_mfma_f32_16x16x32_bf16 v[48:51], v[168:171], v[144:147], v[48:51]
	v_mfma_f32_16x16x32_bf16 v[8:11], v[156:159], v[148:151], v[8:11]
	v_mfma_f32_16x16x32_bf16 v[44:47], v[160:163], v[148:151], v[44:47]
	v_mfma_f32_16x16x32_bf16 v[64:67], v[164:167], v[148:151], v[64:67]
	v_mfma_f32_16x16x32_bf16 v[76:79], v[168:171], v[148:151], v[76:79]
	v_mfma_f32_16x16x32_bf16 v[108:111], v[156:159], v[152:155], v[108:111]
	v_mfma_f32_16x16x32_bf16 v[116:119], v[160:163], v[152:155], v[116:119]
	v_mfma_f32_16x16x32_bf16 v[124:127], v[164:167], v[152:155], v[124:127]
	v_mfma_f32_16x16x32_bf16 v[128:131], v[168:171], v[152:155], v[128:131]
	v_mfma_f32_16x16x32_bf16 v[20:23], v[204:207], v[172:175], v[20:23]
	v_mfma_f32_16x16x32_bf16 v[72:75], v[208:211], v[172:175], v[72:75]
	v_mfma_f32_16x16x32_bf16 v[68:71], v[212:215], v[172:175], v[68:71]
	v_mfma_f32_16x16x32_bf16 v[60:63], v[216:219], v[172:175], v[60:63]
	v_mfma_f32_16x16x32_bf16 v[16:19], v[204:207], v[192:195], v[16:19]
	v_mfma_f32_16x16x32_bf16 v[52:55], v[208:211], v[192:195], v[52:55]
	v_mfma_f32_16x16x32_bf16 v[56:59], v[212:215], v[192:195], v[56:59]
	v_mfma_f32_16x16x32_bf16 v[48:51], v[216:219], v[192:195], v[48:51]
	v_mfma_f32_16x16x32_bf16 v[8:11], v[204:207], v[196:199], v[8:11]
	v_mfma_f32_16x16x32_bf16 v[44:47], v[208:211], v[196:199], v[44:47]
	v_mfma_f32_16x16x32_bf16 v[64:67], v[212:215], v[196:199], v[64:67]
	v_mfma_f32_16x16x32_bf16 v[76:79], v[216:219], v[196:199], v[76:79]
	v_mfma_f32_16x16x32_bf16 v[108:111], v[204:207], v[200:203], v[108:111]
	v_mfma_f32_16x16x32_bf16 v[116:119], v[208:211], v[200:203], v[116:119]
	v_mfma_f32_16x16x32_bf16 v[124:127], v[212:215], v[200:203], v[124:127]
	v_mfma_f32_16x16x32_bf16 v[128:131], v[216:219], v[200:203], v[128:131]
	s_waitcnt vmcnt(0)
	v_mfma_f32_16x16x32_bf16 v[20:23], v[4:7], v[0:3], v[20:23]
	v_mfma_f32_16x16x32_bf16 v[72:75], v[24:27], v[0:3], v[72:75]
	v_mfma_f32_16x16x32_bf16 v[68:71], v[36:39], v[0:3], v[68:71]
	v_mfma_f32_16x16x32_bf16 v[60:63], v[80:83], v[0:3], v[60:63]
	v_mfma_f32_16x16x32_bf16 v[16:19], v[4:7], v[12:15], v[16:19]
	v_mfma_f32_16x16x32_bf16 v[52:55], v[24:27], v[12:15], v[52:55]
	v_mfma_f32_16x16x32_bf16 v[56:59], v[36:39], v[12:15], v[56:59]
	v_mfma_f32_16x16x32_bf16 v[48:51], v[80:83], v[12:15], v[48:51]
	v_mfma_f32_16x16x32_bf16 v[8:11], v[4:7], v[28:31], v[8:11]
	v_mfma_f32_16x16x32_bf16 v[44:47], v[24:27], v[28:31], v[44:47]
	v_mfma_f32_16x16x32_bf16 v[64:67], v[36:39], v[28:31], v[64:67]
	v_mfma_f32_16x16x32_bf16 v[76:79], v[80:83], v[28:31], v[76:79]
	v_mfma_f32_16x16x32_bf16 v[108:111], v[4:7], v[40:43], v[108:111]
	v_mfma_f32_16x16x32_bf16 v[116:119], v[24:27], v[40:43], v[116:119]
	v_mfma_f32_16x16x32_bf16 v[124:127], v[36:39], v[40:43], v[124:127]
	v_mfma_f32_16x16x32_bf16 v[128:131], v[80:83], v[40:43], v[128:131]
	v_mfma_f32_16x16x32_bf16 v[20:23], v[84:87], v[88:91], v[20:23]
	v_mfma_f32_16x16x32_bf16 v[72:75], v[96:99], v[88:91], v[72:75]
	v_mfma_f32_16x16x32_bf16 v[68:71], v[104:107], v[88:91], v[68:71]
	v_mfma_f32_16x16x32_bf16 v[60:63], v[120:123], v[88:91], v[60:63]
	v_mfma_f32_16x16x32_bf16 v[16:19], v[84:87], v[92:95], v[16:19]
	v_mfma_f32_16x16x32_bf16 v[52:55], v[96:99], v[92:95], v[52:55]
	v_mfma_f32_16x16x32_bf16 v[56:59], v[104:107], v[92:95], v[56:59]
	v_mfma_f32_16x16x32_bf16 v[48:51], v[120:123], v[92:95], v[48:51]
	v_mfma_f32_16x16x32_bf16 v[8:11], v[84:87], v[100:103], v[8:11]
	v_mfma_f32_16x16x32_bf16 v[44:47], v[96:99], v[100:103], v[44:47]
	v_mfma_f32_16x16x32_bf16 v[64:67], v[104:107], v[100:103], v[64:67]
	v_mfma_f32_16x16x32_bf16 v[76:79], v[120:123], v[100:103], v[76:79]
	v_mfma_f32_16x16x32_bf16 v[108:111], v[84:87], v[112:115], v[108:111]
	v_mfma_f32_16x16x32_bf16 v[116:119], v[96:99], v[112:115], v[116:119]
	v_mfma_f32_16x16x32_bf16 v[124:127], v[104:107], v[112:115], v[124:127]
	v_mfma_f32_16x16x32_bf16 v[128:131], v[120:123], v[112:115], v[128:131]
	s_nop 7
	s_nop 7
	s_branch .LBB0_5686
